# hand-scheduled SWIGLU epilogue: trans/VALU interleaved, 16-byte stores via v_permlane16_swap; fast f32 rcp division; attention mask mul_i24
# speedup vs baseline: 1.0230x; 1.0183x over previous
.Lswiglu_fast:
	s_lshl_b32 s4, s65, 7
	v_subrev_u32_e32 v168, s4, v162
	v_readlane_b32 s4, v253, 35
	v_readlane_b32 s5, v253, 28
	v_mov_b32_e32 v170, s4
	v_mov_b32_e32 v171, s5
	ds_read_b64 v[174:175], v170
	ds_read_b32 v171, v171
	v_lshlrev_b32_e32 v169, 2, v203
	v_sub_u32_e32 v168, v168, v169
	v_and_b32_e32 v169, 1, v203
	v_lshl_add_u32 v168, v169, 4, v168
	v_lshrrev_b32_e32 v169, 1, v203
	v_lshl_add_u32 v168, v169, 3, v168
	v_ashrrev_i32_e32 v169, 31, v168
	v_mov_b32_e32 v176, 0xbfb8aa3b
	v_mov_b32_e32 v177, 0xbfb8aa3b
	s_waitcnt lgkmcnt(0)
	v_readfirstlane_b32 s5, v171
	v_mad_i64_i32 v[172:173], s[2:3], v171, v160, 0
	v_lshl_add_u64 v[174:175], v[168:169], 1, v[174:175]
	v_lshl_add_u64 v[172:173], v[172:173], 1, v[174:175]
	s_lshl_b32 s6, s5, 5
	s_mov_b32 s7, 0
	s_mul_i32 s8, s6, 5
	s_mov_b32 s9, 0
	v_pk_mul_f32 v[206:207], v[126:127], v[176:177]
	v_exp_f32_e32 v206, v206
	v_pk_mul_f32 v[208:209], v[128:129], v[176:177]
	v_exp_f32_e32 v207, v207
	v_pk_mul_f32 v[210:211], v[118:119], v[176:177]
	v_exp_f32_e32 v208, v208
	v_pk_mul_f32 v[212:213], v[120:121], v[176:177]
	v_exp_f32_e32 v209, v209
	v_pk_add_f32 v[206:207], v[206:207], 1.0 op_sel_hi:[1,0]
	v_exp_f32_e32 v210, v210
	v_pk_add_f32 v[208:209], v[208:209], 1.0 op_sel_hi:[1,0]
	v_exp_f32_e32 v211, v211
	v_pk_mul_f32 v[214:215], v[126:127], v[122:123]
	v_exp_f32_e32 v212, v212
	v_pk_add_f32 v[210:211], v[210:211], 1.0 op_sel_hi:[1,0]
	v_exp_f32_e32 v213, v213
	v_pk_mul_f32 v[216:217], v[128:129], v[124:125]
	v_rcp_f32_e32 v206, v206
	v_pk_add_f32 v[212:213], v[212:213], 1.0 op_sel_hi:[1,0]
	v_rcp_f32_e32 v207, v207
	v_pk_mul_f32 v[218:219], v[118:119], v[114:115]
	v_rcp_f32_e32 v208, v208
	v_pk_mul_f32 v[220:221], v[120:121], v[116:117]
	v_rcp_f32_e32 v209, v209
	v_pk_mul_f32 v[214:215], v[214:215], v[206:207]
	v_rcp_f32_e32 v210, v210
	v_pk_mul_f32 v[216:217], v[216:217], v[208:209]
	v_rcp_f32_e32 v211, v211
	v_cvt_pk_bf16_f32 v222, v214, v215
	v_rcp_f32_e32 v212, v212
	v_pk_mul_f32 v[218:219], v[218:219], v[210:211]
	v_rcp_f32_e32 v213, v213
	v_cvt_pk_bf16_f32 v223, v216, v217
	v_pk_mul_f32 v[220:221], v[220:221], v[212:213]
	v_cvt_pk_bf16_f32 v224, v218, v219
	v_cvt_pk_bf16_f32 v225, v220, v221
	v_pk_mul_f32 v[226:227], v[110:111], v[176:177]
	v_exp_f32_e32 v226, v226
	v_permlane16_swap_b32_e32 v222, v224
	v_exp_f32_e32 v227, v227
	v_permlane16_swap_b32_e32 v223, v225
	global_store_dwordx4 v[172:173], v[222:225], off
	v_pk_mul_f32 v[228:229], v[112:113], v[176:177]
	v_exp_f32_e32 v228, v228
	v_lshl_add_u64 v[172:173], v[172:173], 0, s[6:7]
	v_exp_f32_e32 v229, v229
	v_pk_mul_f32 v[236:237], v[102:103], v[176:177]
	v_exp_f32_e32 v236, v236
	v_pk_mul_f32 v[238:239], v[104:105], v[176:177]
	v_exp_f32_e32 v237, v237
	v_pk_add_f32 v[226:227], v[226:227], 1.0 op_sel_hi:[1,0]
	v_exp_f32_e32 v238, v238
	v_pk_add_f32 v[228:229], v[228:229], 1.0 op_sel_hi:[1,0]
	v_exp_f32_e32 v239, v239
	v_pk_add_f32 v[236:237], v[236:237], 1.0 op_sel_hi:[1,0]
	v_rcp_f32_e32 v226, v226
	v_pk_add_f32 v[238:239], v[238:239], 1.0 op_sel_hi:[1,0]
	v_rcp_f32_e32 v227, v227
	v_pk_mul_f32 v[240:241], v[110:111], v[106:107]
	v_rcp_f32_e32 v228, v228
	v_pk_mul_f32 v[242:243], v[112:113], v[108:109]
	v_rcp_f32_e32 v229, v229
	v_pk_mul_f32 v[244:245], v[102:103], v[98:99]
	v_rcp_f32_e32 v236, v236
	v_pk_mul_f32 v[246:247], v[104:105], v[100:101]
	v_rcp_f32_e32 v237, v237
	v_pk_mul_f32 v[240:241], v[240:241], v[226:227]
	v_rcp_f32_e32 v238, v238
	v_pk_mul_f32 v[242:243], v[242:243], v[228:229]
	v_rcp_f32_e32 v239, v239
	v_pk_mul_f32 v[244:245], v[244:245], v[236:237]
	v_pk_mul_f32 v[246:247], v[246:247], v[238:239]
	v_cvt_pk_bf16_f32 v164, v240, v241
	v_cvt_pk_bf16_f32 v165, v242, v243
	v_cvt_pk_bf16_f32 v166, v244, v245
	v_cvt_pk_bf16_f32 v167, v246, v247
	v_pk_mul_f32 v[130:131], v[94:95], v[176:177]
	v_exp_f32_e32 v130, v130
	v_permlane16_swap_b32_e32 v164, v166
	v_exp_f32_e32 v131, v131
	v_permlane16_swap_b32_e32 v165, v167
	global_store_dwordx4 v[172:173], v[164:167], off
	v_pk_mul_f32 v[132:133], v[96:97], v[176:177]
	v_exp_f32_e32 v132, v132
	v_lshl_add_u64 v[172:173], v[172:173], 0, s[6:7]
	v_exp_f32_e32 v133, v133
	v_pk_mul_f32 v[134:135], v[86:87], v[176:177]
	v_exp_f32_e32 v134, v134
	v_pk_mul_f32 v[136:137], v[88:89], v[176:177]
	v_exp_f32_e32 v135, v135
	v_pk_add_f32 v[130:131], v[130:131], 1.0 op_sel_hi:[1,0]
	v_exp_f32_e32 v136, v136
	v_pk_add_f32 v[132:133], v[132:133], 1.0 op_sel_hi:[1,0]
	v_exp_f32_e32 v137, v137
	v_pk_add_f32 v[134:135], v[134:135], 1.0 op_sel_hi:[1,0]
	v_rcp_f32_e32 v130, v130
	v_pk_add_f32 v[136:137], v[136:137], 1.0 op_sel_hi:[1,0]
	v_rcp_f32_e32 v131, v131
	v_pk_mul_f32 v[138:139], v[94:95], v[90:91]
	v_rcp_f32_e32 v132, v132
	v_pk_mul_f32 v[140:141], v[96:97], v[92:93]
	v_rcp_f32_e32 v133, v133
	v_pk_mul_f32 v[142:143], v[86:87], v[82:83]
	v_rcp_f32_e32 v134, v134
	v_pk_mul_f32 v[144:145], v[88:89], v[84:85]
	v_rcp_f32_e32 v135, v135
	v_pk_mul_f32 v[138:139], v[138:139], v[130:131]
	v_rcp_f32_e32 v136, v136
	v_pk_mul_f32 v[140:141], v[140:141], v[132:133]
	v_rcp_f32_e32 v137, v137
	v_pk_mul_f32 v[142:143], v[142:143], v[134:135]
	v_pk_mul_f32 v[144:145], v[144:145], v[136:137]
	v_cvt_pk_bf16_f32 v146, v138, v139
	v_cvt_pk_bf16_f32 v147, v140, v141
	v_cvt_pk_bf16_f32 v148, v142, v143
	v_cvt_pk_bf16_f32 v149, v144, v145
	v_pk_mul_f32 v[206:207], v[78:79], v[176:177]
	v_exp_f32_e32 v206, v206
	v_permlane16_swap_b32_e32 v146, v148
	v_exp_f32_e32 v207, v207
	v_permlane16_swap_b32_e32 v147, v149
	global_store_dwordx4 v[172:173], v[146:149], off
	v_pk_mul_f32 v[208:209], v[80:81], v[176:177]
	v_exp_f32_e32 v208, v208
	v_lshl_add_u64 v[172:173], v[172:173], 0, s[6:7]
	v_exp_f32_e32 v209, v209
	v_pk_mul_f32 v[210:211], v[70:71], v[176:177]
	v_exp_f32_e32 v210, v210
	v_pk_mul_f32 v[212:213], v[72:73], v[176:177]
	v_exp_f32_e32 v211, v211
	v_pk_add_f32 v[206:207], v[206:207], 1.0 op_sel_hi:[1,0]
	v_exp_f32_e32 v212, v212
	v_pk_add_f32 v[208:209], v[208:209], 1.0 op_sel_hi:[1,0]
	v_exp_f32_e32 v213, v213
	v_pk_add_f32 v[210:211], v[210:211], 1.0 op_sel_hi:[1,0]
	v_rcp_f32_e32 v206, v206
	v_pk_add_f32 v[212:213], v[212:213], 1.0 op_sel_hi:[1,0]
	v_rcp_f32_e32 v207, v207
	v_pk_mul_f32 v[214:215], v[78:79], v[74:75]
	v_rcp_f32_e32 v208, v208
	v_pk_mul_f32 v[216:217], v[80:81], v[76:77]
	v_rcp_f32_e32 v209, v209
	v_pk_mul_f32 v[218:219], v[70:71], v[66:67]
	v_rcp_f32_e32 v210, v210
	v_pk_mul_f32 v[220:221], v[72:73], v[68:69]
	v_rcp_f32_e32 v211, v211
	v_pk_mul_f32 v[214:215], v[214:215], v[206:207]
	v_rcp_f32_e32 v212, v212
	v_pk_mul_f32 v[216:217], v[216:217], v[208:209]
	v_rcp_f32_e32 v213, v213
	v_pk_mul_f32 v[218:219], v[218:219], v[210:211]
	v_pk_mul_f32 v[220:221], v[220:221], v[212:213]
	v_cvt_pk_bf16_f32 v222, v214, v215
	v_cvt_pk_bf16_f32 v223, v216, v217
	v_cvt_pk_bf16_f32 v224, v218, v219
	v_cvt_pk_bf16_f32 v225, v220, v221
	v_pk_mul_f32 v[226:227], v[62:63], v[176:177]
	v_exp_f32_e32 v226, v226
	v_permlane16_swap_b32_e32 v222, v224
	v_exp_f32_e32 v227, v227
	v_permlane16_swap_b32_e32 v223, v225
	global_store_dwordx4 v[172:173], v[222:225], off
	v_pk_mul_f32 v[228:229], v[64:65], v[176:177]
	v_exp_f32_e32 v228, v228
	v_lshl_add_u64 v[172:173], v[172:173], 0, s[8:9]
	v_exp_f32_e32 v229, v229
	v_pk_mul_f32 v[236:237], v[54:55], v[176:177]
	v_exp_f32_e32 v236, v236
	v_pk_mul_f32 v[238:239], v[56:57], v[176:177]
	v_exp_f32_e32 v237, v237
	v_pk_add_f32 v[226:227], v[226:227], 1.0 op_sel_hi:[1,0]
	v_exp_f32_e32 v238, v238
	v_pk_add_f32 v[228:229], v[228:229], 1.0 op_sel_hi:[1,0]
	v_exp_f32_e32 v239, v239
	v_pk_add_f32 v[236:237], v[236:237], 1.0 op_sel_hi:[1,0]
	v_rcp_f32_e32 v226, v226
	v_pk_add_f32 v[238:239], v[238:239], 1.0 op_sel_hi:[1,0]
	v_rcp_f32_e32 v227, v227
	v_pk_mul_f32 v[240:241], v[62:63], v[58:59]
	v_rcp_f32_e32 v228, v228
	v_pk_mul_f32 v[242:243], v[64:65], v[60:61]
	v_rcp_f32_e32 v229, v229
	v_pk_mul_f32 v[244:245], v[54:55], v[50:51]
	v_rcp_f32_e32 v236, v236
	v_pk_mul_f32 v[246:247], v[56:57], v[52:53]
	v_rcp_f32_e32 v237, v237
	v_pk_mul_f32 v[240:241], v[240:241], v[226:227]
	v_rcp_f32_e32 v238, v238
	v_pk_mul_f32 v[242:243], v[242:243], v[228:229]
	v_rcp_f32_e32 v239, v239
	v_pk_mul_f32 v[244:245], v[244:245], v[236:237]
	v_pk_mul_f32 v[246:247], v[246:247], v[238:239]
	v_cvt_pk_bf16_f32 v164, v240, v241
	v_cvt_pk_bf16_f32 v165, v242, v243
	v_cvt_pk_bf16_f32 v166, v244, v245
	v_cvt_pk_bf16_f32 v167, v246, v247
	v_pk_mul_f32 v[130:131], v[46:47], v[176:177]
	v_exp_f32_e32 v130, v130
	v_permlane16_swap_b32_e32 v164, v166
	v_exp_f32_e32 v131, v131
	v_permlane16_swap_b32_e32 v165, v167
	global_store_dwordx4 v[172:173], v[164:167], off
	v_pk_mul_f32 v[132:133], v[48:49], v[176:177]
	v_exp_f32_e32 v132, v132
	v_lshl_add_u64 v[172:173], v[172:173], 0, s[6:7]
	v_exp_f32_e32 v133, v133
	v_pk_mul_f32 v[134:135], v[38:39], v[176:177]
	v_exp_f32_e32 v134, v134
	v_pk_mul_f32 v[136:137], v[40:41], v[176:177]
	v_exp_f32_e32 v135, v135
	v_pk_add_f32 v[130:131], v[130:131], 1.0 op_sel_hi:[1,0]
	v_exp_f32_e32 v136, v136
	v_pk_add_f32 v[132:133], v[132:133], 1.0 op_sel_hi:[1,0]
	v_exp_f32_e32 v137, v137
	v_pk_add_f32 v[134:135], v[134:135], 1.0 op_sel_hi:[1,0]
	v_rcp_f32_e32 v130, v130
	v_pk_add_f32 v[136:137], v[136:137], 1.0 op_sel_hi:[1,0]
	v_rcp_f32_e32 v131, v131
	v_pk_mul_f32 v[138:139], v[46:47], v[42:43]
	v_rcp_f32_e32 v132, v132
	v_pk_mul_f32 v[140:141], v[48:49], v[44:45]
	v_rcp_f32_e32 v133, v133
	v_pk_mul_f32 v[142:143], v[38:39], v[34:35]
	v_rcp_f32_e32 v134, v134
	v_pk_mul_f32 v[144:145], v[40:41], v[36:37]
	v_rcp_f32_e32 v135, v135
	v_pk_mul_f32 v[138:139], v[138:139], v[130:131]
	v_rcp_f32_e32 v136, v136
	v_pk_mul_f32 v[140:141], v[140:141], v[132:133]
	v_rcp_f32_e32 v137, v137
	v_pk_mul_f32 v[142:143], v[142:143], v[134:135]
	v_pk_mul_f32 v[144:145], v[144:145], v[136:137]
	v_cvt_pk_bf16_f32 v146, v138, v139
	v_cvt_pk_bf16_f32 v147, v140, v141
	v_cvt_pk_bf16_f32 v148, v142, v143
	v_cvt_pk_bf16_f32 v149, v144, v145
	v_pk_mul_f32 v[206:207], v[30:31], v[176:177]
	v_exp_f32_e32 v206, v206
	v_permlane16_swap_b32_e32 v146, v148
	v_exp_f32_e32 v207, v207
	v_permlane16_swap_b32_e32 v147, v149
	global_store_dwordx4 v[172:173], v[146:149], off
	v_pk_mul_f32 v[208:209], v[32:33], v[176:177]
	v_exp_f32_e32 v208, v208
	v_lshl_add_u64 v[172:173], v[172:173], 0, s[6:7]
	v_exp_f32_e32 v209, v209
	v_pk_mul_f32 v[210:211], v[22:23], v[176:177]
	v_exp_f32_e32 v210, v210
	v_pk_mul_f32 v[212:213], v[24:25], v[176:177]
	v_exp_f32_e32 v211, v211
	v_pk_add_f32 v[206:207], v[206:207], 1.0 op_sel_hi:[1,0]
	v_exp_f32_e32 v212, v212
	v_pk_add_f32 v[208:209], v[208:209], 1.0 op_sel_hi:[1,0]
	v_exp_f32_e32 v213, v213
	v_pk_add_f32 v[210:211], v[210:211], 1.0 op_sel_hi:[1,0]
	v_rcp_f32_e32 v206, v206
	v_pk_add_f32 v[212:213], v[212:213], 1.0 op_sel_hi:[1,0]
	v_rcp_f32_e32 v207, v207
	v_pk_mul_f32 v[214:215], v[30:31], v[26:27]
	v_rcp_f32_e32 v208, v208
	v_pk_mul_f32 v[216:217], v[32:33], v[28:29]
	v_rcp_f32_e32 v209, v209
	v_pk_mul_f32 v[218:219], v[22:23], v[18:19]
	v_rcp_f32_e32 v210, v210
	v_pk_mul_f32 v[220:221], v[24:25], v[20:21]
	v_rcp_f32_e32 v211, v211
	v_pk_mul_f32 v[214:215], v[214:215], v[206:207]
	v_rcp_f32_e32 v212, v212
	v_pk_mul_f32 v[216:217], v[216:217], v[208:209]
	v_rcp_f32_e32 v213, v213
	v_pk_mul_f32 v[218:219], v[218:219], v[210:211]
	v_pk_mul_f32 v[220:221], v[220:221], v[212:213]
	v_cvt_pk_bf16_f32 v222, v214, v215
	v_cvt_pk_bf16_f32 v223, v216, v217
	v_cvt_pk_bf16_f32 v224, v218, v219
	v_cvt_pk_bf16_f32 v225, v220, v221
	v_pk_mul_f32 v[226:227], v[14:15], v[176:177]
	v_exp_f32_e32 v226, v226
	v_permlane16_swap_b32_e32 v222, v224
	v_exp_f32_e32 v227, v227
	v_permlane16_swap_b32_e32 v223, v225
	global_store_dwordx4 v[172:173], v[222:225], off
	v_pk_mul_f32 v[228:229], v[16:17], v[176:177]
	v_exp_f32_e32 v228, v228
	v_lshl_add_u64 v[172:173], v[172:173], 0, s[6:7]
	v_exp_f32_e32 v229, v229
	v_pk_mul_f32 v[236:237], v[6:7], v[176:177]
	v_exp_f32_e32 v236, v236
	v_pk_mul_f32 v[238:239], v[8:9], v[176:177]
	v_exp_f32_e32 v237, v237
	v_pk_add_f32 v[226:227], v[226:227], 1.0 op_sel_hi:[1,0]
	v_exp_f32_e32 v238, v238
	v_pk_add_f32 v[228:229], v[228:229], 1.0 op_sel_hi:[1,0]
	v_exp_f32_e32 v239, v239
	v_pk_add_f32 v[236:237], v[236:237], 1.0 op_sel_hi:[1,0]
	v_rcp_f32_e32 v226, v226
	v_pk_add_f32 v[238:239], v[238:239], 1.0 op_sel_hi:[1,0]
	v_rcp_f32_e32 v227, v227
	v_pk_mul_f32 v[240:241], v[14:15], v[10:11]
	v_rcp_f32_e32 v228, v228
	v_pk_mul_f32 v[242:243], v[16:17], v[12:13]
	v_rcp_f32_e32 v229, v229
	v_pk_mul_f32 v[244:245], v[6:7], v[2:3]
	v_rcp_f32_e32 v236, v236
	v_pk_mul_f32 v[246:247], v[8:9], v[4:5]
	v_rcp_f32_e32 v237, v237
	v_pk_mul_f32 v[240:241], v[240:241], v[226:227]
	v_rcp_f32_e32 v238, v238
	v_pk_mul_f32 v[242:243], v[242:243], v[228:229]
	v_rcp_f32_e32 v239, v239
	v_pk_mul_f32 v[244:245], v[244:245], v[236:237]
	v_pk_mul_f32 v[246:247], v[246:247], v[238:239]
	v_cvt_pk_bf16_f32 v164, v240, v241
	v_cvt_pk_bf16_f32 v165, v242, v243
	v_cvt_pk_bf16_f32 v166, v244, v245
	v_cvt_pk_bf16_f32 v167, v246, v247
	s_nop 0
	v_permlane16_swap_b32_e32 v164, v166
	v_permlane16_swap_b32_e32 v165, v167
	global_store_dwordx4 v[172:173], v[164:167], off
	s_branch .LBB0_816
